# attention: K-tile LDS writes issued before barrier 1 (target buffer is idle during the step); only the V-tile writes remain between the barriers
# speedup vs baseline: 1.0345x; 1.0091x over previous
; __device__ __forceinline__ void finishSM(f32x16& p0, f32x16& p1, float alpha, float& l_reg, bf16x8& pa0, bf16x8& pa1, bf16x8& pa2, bf16x8& pa3) {
; #pragma unroll
;     for (int r = 0; r < 16; ++r) p1[r] = __builtin_amdgcn_exp2f(p1[r]);
;     float ps = 0;
; #pragma unroll
;     for (int r = 0; r < 16; ++r) ps += p0[r];
; #pragma unroll
;     for (int r = 0; r < 16; ++r) ps += p1[r];
;     { auto rr = __builtin_amdgcn_permlane32_swap(__float_as_uint(ps), __float_as_uint(ps), false, false);
;       ps = __uint_as_float(rr[0]) + __uint_as_float(rr[1]); }
;     l_reg = l_reg * alpha + ps;
;     ...
;     PK4(p0, 0, pa0); PK4(p0, 8, pa1); PK4(p1, 0, pa2); PK4(p1, 8, pa3);
;     ...
; }
; template <int KB>
; __device__ __forceinline__ void qkt(f32x16& p0, f32x16& p1, const char* K_lds, int r32, int hi, const bf16x8* qr) {
;     p0 = f32x16{}; p1 = f32x16{};
;     const char* kb[4];
; #pragma unroll
;     for (int dd = 0; dd < 4; ++dd) kb[dd] = K_lds + KB * SHM_K + KSWZ(r32, (dd * 16 + hi * 8) * 2);
; #pragma unroll
;     for (int d0 = 0; d0 < 8; ++d0) { const char* a = kb[d0 & 3] + (d0 >> 2) * 128;
;         bf16x8 b0 = *reinterpret_cast<const bf16x8*>(a);
;         bf16x8 b1 = *reinterpret_cast<const bf16x8*>(a + 32 * 256);
;         p0 = __builtin_amdgcn_mfma_f32_32x32x16_bf16(b0, qr[d0], p0, 0, 0, 0);
;         p1 = __builtin_amdgcn_mfma_f32_32x32x16_bf16(b1, qr[d0], p1, 0, 0, 0); }
; }
.LBB0_1299:
	v_add_u32_e32 v146, -8, v179
	global_load_dwordx2 v[146:147], v146, s[68:69]
	v_lshl_add_u64 v[130:131], v[188:189], 0, v[170:171]
	v_lshl_add_u64 v[138:139], v[190:191], 0, v[170:171]
	v_lshl_add_u64 v[134:135], v[130:131], 0, s[100:101]
	v_lshl_add_u64 v[130:131], v[130:131], 0, s[16:17]
	v_lshl_add_u64 v[142:143], v[138:139], 0, s[100:101]
	v_lshl_add_u64 v[138:139], v[138:139], 0, s[16:17]
	global_load_dwordx4 v[130:133], v[130:131], off
	global_load_dwordx4 v[134:137], v[134:135], off
	global_load_dwordx4 v[138:141], v[138:139], off
	global_load_dwordx4 v[142:145], v[142:143], off
	ds_read_b128 v[66:69], v199 offset:49152
	ds_read_b128 v[82:85], v199 offset:57344
	ds_read_b128 v[172:175], v200 offset:49152
	ds_read_b128 v[232:235], v200 offset:57344
	ds_read_b128 v[236:239], v201 offset:49152
	ds_read_b128 v[240:243], v201 offset:57344
	ds_read_b128 v[244:247], v202 offset:49152
	v_exp_f32_e32 v209, v150
	v_add_f32_e32 v150, 0, v219
	v_add_f32_e32 v150, v220, v150
	v_add_f32_e32 v150, v221, v150
	s_waitcnt lgkmcnt(6)
	v_mfma_f32_32x32x16_bf16 v[66:81], v[66:69], v[126:129], 0
	v_add_f32_e32 v150, v222, v150
	v_add_f32_e32 v150, v223, v150
	v_add_f32_e32 v150, v225, v150
	v_add_f32_e32 v150, v224, v150
	v_add_f32_e32 v150, v226, v150
	s_waitcnt lgkmcnt(5)
	v_mfma_f32_32x32x16_bf16 v[82:97], v[82:85], v[126:129], 0
	v_add_f32_e32 v150, v211, v150
	v_add_f32_e32 v150, v212, v150
	v_exp_f32_e32 v194, v194
	s_waitcnt lgkmcnt(4)
	v_mfma_f32_32x32x16_bf16 v[66:81], v[172:175], v[122:125], v[66:81]
	ds_read_b128 v[172:175], v202 offset:57344
	v_exp_f32_e32 v195, v195
	v_exp_f32_e32 v192, v192
	v_exp_f32_e32 v193, v193
	s_waitcnt lgkmcnt(4)
	v_mfma_f32_32x32x16_bf16 v[82:97], v[232:235], v[122:125], v[82:97]
	ds_read_b128 v[232:235], v199 offset:49280
	v_exp_f32_e32 v158, v158
	v_exp_f32_e32 v159, v159
	s_waitcnt lgkmcnt(4)
	v_mfma_f32_32x32x16_bf16 v[66:81], v[236:239], v[118:121], v[66:81]
	ds_read_b128 v[236:239], v199 offset:57472
	v_exp_f32_e32 v207, v154
	v_exp_f32_e32 v208, v155
	v_exp_f32_e32 v210, v151
	s_waitcnt lgkmcnt(4)
	v_mfma_f32_32x32x16_bf16 v[82:97], v[240:243], v[118:121], v[82:97]
	ds_read_b128 v[240:243], v200 offset:49280
	v_exp_f32_e32 v160, v160
	v_exp_f32_e32 v161, v161
	s_waitcnt lgkmcnt(4)
	v_mfma_f32_32x32x16_bf16 v[66:81], v[244:247], v[114:117], v[66:81]
	ds_read_b128 v[244:247], v200 offset:57472
	v_exp_f32_e32 v227, v156
	v_cvt_pk_bf16_f32 v151, v224, v226
	v_cvt_pk_bf16_f32 v154, v214, v216
	v_cvt_pk_bf16_f32 v155, v217, v218
	v_cvt_pk_bf16_f32 v156, v194, v195
	s_waitcnt lgkmcnt(4)
	v_mfma_f32_32x32x16_bf16 v[82:97], v[172:175], v[114:117], v[82:97]
	ds_read_b128 v[172:175], v201 offset:49280
	v_exp_f32_e32 v228, v157
	v_exp_f32_e32 v229, v152
	s_waitcnt lgkmcnt(4)
	v_mfma_f32_32x32x16_bf16 v[66:81], v[232:235], v[110:113], v[66:81]
	ds_read_b128 v[232:235], v201 offset:57472
	v_exp_f32_e32 v230, v153
	v_cvt_pk_bf16_f32 v152, v211, v212
	v_cvt_pk_bf16_f32 v153, v213, v215
	v_cvt_pk_bf16_f32 v157, v192, v193
	v_cvt_pk_bf16_f32 v211, v229, v230
	s_waitcnt lgkmcnt(4)
	v_mfma_f32_32x32x16_bf16 v[82:97], v[236:239], v[110:113], v[82:97]
	ds_read_b128 v[236:239], v202 offset:49280
	v_permlane32_swap_b32_e32 v152, v154
	v_permlane32_swap_b32_e32 v153, v155
	v_add_f32_e32 v249, v213, v150
	v_add_f32_e32 v249, v215, v249
	v_add_f32_e32 v249, v214, v249
	s_waitcnt lgkmcnt(4)
	v_mfma_f32_32x32x16_bf16 v[66:81], v[240:243], v[106:109], v[66:81]
	ds_read_b128 v[240:243], v202 offset:57472
	v_add_f32_e32 v249, v216, v249
	v_add_f32_e32 v249, v217, v249
	v_add_f32_e32 v249, v218, v249
	v_add_f32_e32 v249, v194, v249
	v_add_f32_e32 v248, v195, v249
	s_waitcnt lgkmcnt(4)
	v_mfma_f32_32x32x16_bf16 v[82:97], v[244:247], v[106:109], v[82:97]
	v_add_f32_e32 v248, v192, v248
	v_add_f32_e32 v248, v193, v248
	v_add_f32_e32 v248, v158, v248
	v_add_f32_e32 v248, v159, v248
	v_add_f32_e32 v248, v207, v248
	s_waitcnt lgkmcnt(3)
	v_mfma_f32_32x32x16_bf16 v[66:81], v[172:175], v[102:105], v[66:81]
	v_add_f32_e32 v248, v208, v248
	v_add_f32_e32 v248, v209, v248
	v_add_f32_e32 v248, v210, v248
	v_add_f32_e32 v248, v160, v248
	v_add_f32_e32 v248, v161, v248
	s_waitcnt lgkmcnt(2)
	v_mfma_f32_32x32x16_bf16 v[82:97], v[232:235], v[102:105], v[82:97]
	v_add_f32_e32 v248, v227, v248
	v_add_f32_e32 v248, v228, v248
	v_add_f32_e32 v248, v229, v248
	v_add_f32_e32 v181, v230, v248
	v_mov_b32_e32 v187, v181
	s_waitcnt lgkmcnt(1)
	v_mfma_f32_32x32x16_bf16 v[66:81], v[236:239], v[98:101], v[66:81]
	v_cvt_pk_bf16_f32 v148, v219, v220
	v_cvt_pk_bf16_f32 v149, v221, v222
	v_cvt_pk_bf16_f32 v150, v223, v225
	v_cvt_pk_bf16_f32 v158, v158, v159
	v_cvt_pk_bf16_f32 v159, v207, v208
	s_waitcnt lgkmcnt(0)
	v_mfma_f32_32x32x16_bf16 v[82:97], v[240:243], v[98:101], v[82:97]
	v_cvt_pk_bf16_f32 v208, v209, v210
	v_cvt_pk_bf16_f32 v210, v227, v228
	v_permlane32_swap_b32_e32 v181, v187
	v_permlane32_swap_b32_e32 v148, v150
	v_permlane32_swap_b32_e32 v149, v151
	v_cvt_pk_bf16_f32 v209, v160, v161
	v_permlane32_swap_b32_e32 v208, v210
	v_permlane32_swap_b32_e32 v156, v158
	v_permlane32_swap_b32_e32 v157, v159
	v_permlane32_swap_b32_e32 v209, v211
	v_lshl_add_u64 v[194:195], v[188:189], 0, v[170:171]
	v_lshl_add_u64 v[192:193], v[190:191], 0, v[170:171]
	ds_read_b64_tr_b16 v[172:173], v1 offset:0x0
	ds_read_b64_tr_b16 v[174:175], v1 offset:0x800
	ds_read_b64_tr_b16 v[212:213], v1 offset:0x200
	ds_read_b64_tr_b16 v[214:215], v1 offset:0xa00
	ds_read_b64_tr_b16 v[216:217], v1 offset:0x400
	ds_read_b64_tr_b16 v[218:219], v1 offset:0xc00
	ds_read_b64_tr_b16 v[220:221], v1 offset:0x600
	ds_read_b64_tr_b16 v[222:223], v1 offset:0xe00
	ds_read_b64_tr_b16 v[224:225], v1 offset:0x1000
	ds_read_b64_tr_b16 v[226:227], v1 offset:0x1800
	ds_read_b64_tr_b16 v[232:233], v1 offset:0x1200
	ds_read_b64_tr_b16 v[234:235], v1 offset:0x1a00
	ds_read_b64_tr_b16 v[236:237], v1 offset:0x1400
	ds_read_b64_tr_b16 v[238:239], v1 offset:0x1c00
	s_nop 0
	s_waitcnt lgkmcnt(12)
; __device__ __forceinline__ void sel_mask_tile(f32x16& p0, f32x16& p1, unsigned wlo, unsigned whi, int hi) {
;     const unsigned NEGB = 0xff800000u;
;     const unsigned lo = wlo >> (4 * hi), h2 = whi >> (4 * hi);
; #pragma unroll
;     for (int r = 0; r < 16; ++r) {
;         const int c = (r & 3) + 8 * (r >> 2);
;         const unsigned m0 = (unsigned)__builtin_amdgcn_sbfe((int)lo, c, 1), m1 = (unsigned)__builtin_amdgcn_sbfe((int)h2, c, 1);
;         p0[r] = __uint_as_float((__float_as_uint(p0[r]) & m0) | (NEGB & ~m0));
;         p1[r] = __uint_as_float((__float_as_uint(p1[r]) & m1) | (NEGB & ~m1));
;     }
; }
; __device__ __forceinline__ void partialSM(f32x16& p0, f32x16& p1, float& m_reg, float& mn, float& alpha) {
;     float pmax = p0[0];
; #pragma unroll
;     for (int r = 1; r < 16; ++r) pmax = fmaxf(pmax, p0[r]);
; #pragma unroll
;     for (int r = 0; r < 16; ++r) pmax = fmaxf(pmax, p1[r]);
;     { auto rr = __builtin_amdgcn_permlane32_swap(__float_as_uint(pmax), __float_as_uint(pmax), false, false);
;       pmax = fmaxf(__uint_as_float(rr[0]), __uint_as_float(rr[1])); }
;     constexpr float C2 = 1.4426950408889634f * SCALE;
;     if (__builtin_expect(__all((pmax - m_reg) * SCALE <= THR), 1)) { mn = m_reg; alpha = 1.f; }
;     else { mn = fmaxf(m_reg, pmax); alpha = __builtin_amdgcn_exp2f((m_reg - mn) * C2); m_reg = mn; }
; template <int VB>
; __device__ __forceinline__ void pv_tile(f32x16* o, int vb0, bf16x8 pa0, bf16x8 pa1, bf16x8 pa2, bf16x8 pa3) {
;     ...
;     PV_D0(0); PV_D0(1); PV_D0(2); PV_D0(3);
;     ...
; }
	v_mfma_f32_32x32x16_bf16 v[2:17], v[148:151], v[172:175], v[2:17]
	ds_read_b64_tr_b16 v[240:241], v1 offset:0x1600
	ds_read_b64_tr_b16 v[242:243], v1 offset:0x1e00
	s_waitcnt vmcnt(4)
	v_lshrrev_b32_e32 v160, v163, v146
	v_lshrrev_b32_e32 v161, v163, v147
	v_bfe_i32 v146, v160, 0, 1
	v_bfe_i32 v147, v161, 0, 1
	v_bitop3_b32 v146, v66, s74, v146 bitop3:0xe4
	v_bitop3_b32 v66, v82, s74, v147 bitop3:0xe4
	s_waitcnt lgkmcnt(12)
	v_mfma_f32_32x32x16_bf16 v[50:65], v[148:151], v[212:215], v[50:65]
	ds_read_b64_tr_b16 v[244:245], v1 offset:0x2000
	ds_read_b64_tr_b16 v[246:247], v1 offset:0x2800
	v_bfe_i32 v82, v160, 1, 1
	v_bfe_i32 v147, v161, 1, 1
	v_bitop3_b32 v82, v67, s74, v82 bitop3:0xe4
	v_bitop3_b32 v67, v83, s74, v147 bitop3:0xe4
	v_bfe_i32 v83, v160, 2, 1
	v_bfe_i32 v147, v161, 2, 1
	s_waitcnt lgkmcnt(12)
	v_mfma_f32_32x32x16_bf16 v[34:49], v[148:151], v[216:219], v[34:49]
	ds_read_b64_tr_b16 v[248:249], v1 offset:0x2200
	ds_read_b64_tr_b16 v[250:251], v1 offset:0x2a00
	v_bitop3_b32 v83, v68, s74, v83 bitop3:0xe4
	v_bitop3_b32 v68, v84, s74, v147 bitop3:0xe4
	v_bfe_i32 v84, v160, 3, 1
	s_waitcnt lgkmcnt(12)
	v_mfma_f32_32x32x16_bf16 v[18:33], v[148:151], v[220:223], v[18:33]
	ds_read_b64_tr_b16 v[220:221], v1 offset:0x2400
	ds_read_b64_tr_b16 v[222:223], v1 offset:0x2c00
	v_bfe_i32 v148, v161, 3, 1
	v_bitop3_b32 v147, v69, s74, v84 bitop3:0xe4
	v_bfe_i32 v84, v160, 8, 1
	v_bitop3_b32 v69, v85, s74, v148 bitop3:0xe4
	v_bfe_i32 v85, v161, 8, 1
	v_bitop3_b32 v148, v70, s74, v84 bitop3:0xe4
	v_bfe_i32 v84, v160, 9, 1
	s_waitcnt lgkmcnt(12)
	v_mfma_f32_32x32x16_bf16 v[2:17], v[152:155], v[224:227], v[2:17]
	ds_read_b64_tr_b16 v[224:225], v1 offset:0x2600
	ds_read_b64_tr_b16 v[226:227], v1 offset:0x2e00
	v_bitop3_b32 v70, v86, s74, v85 bitop3:0xe4
	v_bfe_i32 v85, v161, 9, 1
	v_bitop3_b32 v149, v71, s74, v84 bitop3:0xe4
	v_bfe_i32 v84, v160, 10, 1
	v_bitop3_b32 v71, v87, s74, v85 bitop3:0xe4
	v_bfe_i32 v85, v161, 10, 1
	s_waitcnt lgkmcnt(12)
	v_mfma_f32_32x32x16_bf16 v[50:65], v[152:155], v[232:235], v[50:65]
	ds_read_b64_tr_b16 v[232:233], v1 offset:0x3000
	ds_read_b64_tr_b16 v[234:235], v1 offset:0x3800
	v_bitop3_b32 v87, v72, s74, v84 bitop3:0xe4
	v_bfe_i32 v84, v160, 11, 1
	v_bitop3_b32 v72, v88, s74, v85 bitop3:0xe4
	v_bfe_i32 v85, v161, 11, 1
	v_bitop3_b32 v88, v73, s74, v84 bitop3:0xe4
	v_bfe_i32 v73, v160, 16, 1
	v_bitop3_b32 v84, v89, s74, v85 bitop3:0xe4
	s_waitcnt lgkmcnt(12)
	v_mfma_f32_32x32x16_bf16 v[34:49], v[152:155], v[236:239], v[34:49]
	ds_read_b64_tr_b16 v[236:237], v1 offset:0x3200
	ds_read_b64_tr_b16 v[238:239], v1 offset:0x3a00
	v_bfe_i32 v85, v161, 16, 1
	v_bitop3_b32 v89, v74, s74, v73 bitop3:0xe4
	v_bfe_i32 v73, v160, 17, 1
	v_bfe_i32 v74, v161, 17, 1
	v_bitop3_b32 v85, v90, s74, v85 bitop3:0xe4
	v_bitop3_b32 v90, v75, s74, v73 bitop3:0xe4
	s_waitcnt lgkmcnt(12)
	v_mfma_f32_32x32x16_bf16 v[18:33], v[152:155], v[240:243], v[18:33]
	ds_read_b64_tr_b16 v[240:241], v1 offset:0x3400
	ds_read_b64_tr_b16 v[242:243], v1 offset:0x3c00
	v_bitop3_b32 v86, v91, s74, v74 bitop3:0xe4
	v_bfe_i32 v73, v160, 18, 1
	v_bfe_i32 v74, v161, 18, 1
	v_bitop3_b32 v91, v76, s74, v73 bitop3:0xe4
	v_bitop3_b32 v76, v92, s74, v74 bitop3:0xe4
	v_bfe_i32 v73, v160, 19, 1
	v_bfe_i32 v74, v161, 19, 1
	s_waitcnt lgkmcnt(12)
	v_mfma_f32_32x32x16_bf16 v[2:17], v[156:159], v[244:247], v[2:17]
	ds_read_b64_tr_b16 v[244:245], v1 offset:0x3600
	ds_read_b64_tr_b16 v[246:247], v1 offset:0x3e00
	v_bitop3_b32 v92, v77, s74, v73 bitop3:0xe4
	v_bitop3_b32 v77, v93, s74, v74 bitop3:0xe4
	v_bfe_i32 v73, v160, 24, 1
	v_bfe_i32 v74, v161, 24, 1
	v_bitop3_b32 v93, v78, s74, v73 bitop3:0xe4
	v_bitop3_b32 v78, v94, s74, v74 bitop3:0xe4
	s_waitcnt lgkmcnt(12)
	v_mfma_f32_32x32x16_bf16 v[50:65], v[156:159], v[248:251], v[50:65]
	v_bfe_i32 v73, v160, 25, 1
	v_bfe_i32 v74, v161, 25, 1
	v_bitop3_b32 v79, v79, s74, v73 bitop3:0xe4
	v_bitop3_b32 v73, v95, s74, v74 bitop3:0xe4
	v_bfe_i32 v74, v160, 26, 1
	v_bfe_i32 v75, v161, 26, 1
	v_bitop3_b32 v80, v80, s74, v74 bitop3:0xe4
	s_waitcnt lgkmcnt(10)
	v_mfma_f32_32x32x16_bf16 v[34:49], v[156:159], v[220:223], v[34:49]
	v_bitop3_b32 v74, v96, s74, v75 bitop3:0xe4
	v_bfe_i32 v75, v160, 27, 1
	v_bfe_i32 v94, v161, 27, 1
	v_bitop3_b32 v81, v81, s74, v75 bitop3:0xe4
	v_bitop3_b32 v75, v97, s74, v94 bitop3:0xe4
	v_max_f32_e32 v94, v82, v82
	s_waitcnt lgkmcnt(8)
	v_mfma_f32_32x32x16_bf16 v[18:33], v[156:159], v[224:227], v[18:33]
	v_max_f32_e32 v95, v146, v146
	v_max_f32_e32 v94, v95, v94
	v_max3_f32 v94, v94, v83, v147
	v_max3_f32 v94, v94, v148, v149
	v_max3_f32 v94, v94, v87, v88
	v_max3_f32 v94, v94, v89, v90
	v_max3_f32 v94, v94, v91, v92
	s_waitcnt lgkmcnt(6)
	v_mfma_f32_32x32x16_bf16 v[2:17], v[208:211], v[232:235], v[2:17]
	v_max3_f32 v94, v94, v93, v79
	v_max3_f32 v94, v94, v80, v81
	v_max3_f32 v94, v94, v66, v67
	v_max3_f32 v94, v94, v68, v69
	v_max3_f32 v94, v94, v70, v71
	v_max3_f32 v94, v94, v72, v84
	s_waitcnt lgkmcnt(4)
	v_mfma_f32_32x32x16_bf16 v[50:65], v[208:211], v[236:239], v[50:65]
	v_max3_f32 v94, v94, v85, v86
	v_max3_f32 v94, v94, v76, v77
	v_max3_f32 v94, v94, v78, v73
	v_max3_f32 v94, v94, v74, v75
	v_mov_b32_e32 v95, v94
	s_nop 1
	v_permlane32_swap_b32_e32 v94, v95
	s_waitcnt lgkmcnt(2)
	v_mfma_f32_32x32x16_bf16 v[34:49], v[208:211], v[240:243], v[34:49]
	v_max_f32_e32 v95, v95, v95
	v_max_f32_e32 v94, v94, v94
	v_max_f32_e32 v94, v94, v95
	v_max_f32_e32 v96, v206, v206
	v_sub_f32_e32 v95, v94, v206
	v_max_f32_e32 v94, v96, v94
	v_sub_f32_e32 v96, v206, v94
	s_waitcnt lgkmcnt(0)
	v_mfma_f32_32x32x16_bf16 v[18:33], v[208:211], v[244:247], v[18:33]
	s_waitcnt vmcnt(0)
	ds_write_b128 v204, v[138:141] offset:32768
	ds_write_b128 v204, v[142:145] offset:40960
	v_mul_f32_e32 v96, 0x3e0293ee, v96
	v_mul_f32_e32 v95, 0x3db504f3, v95
	v_exp_f32_e32 v96, v96
	v_cmp_ge_f32_e32 vcc, s75, v95
	s_cmp_eq_u64 vcc, exec
	s_cselect_b64 s[6:7], -1, 0
	s_barrier
	s_waitcnt vmcnt(0)
	v_cndmask_b32_e64 v208, v96, 1.0, s[6:7]
	v_cmp_gt_f32_e32 vcc, 1.0, v208
	ds_write_b128 v197, v[130:133]
	ds_write_b128 v198, v[134:137]
	s_cbranch_vccz .LBB0_1303
	s_and_saveexec_b64 s[36:37], s[0:1]
	ds_write_b32 v185, v208 offset:128
	s_or_b64 exec, exec, s[36:37]
	s_waitcnt lgkmcnt(0)
	ds_read_b128 v[150:153], v183 offset:224
	ds_read_b128 v[154:157], v183 offset:192
	ds_read_b128 v[158:161], v183 offset:160
	ds_read_b128 v[172:175], v183 offset:128
	s_waitcnt lgkmcnt(3)
	v_pk_mul_f32 v[16:17], v[16:17], v[152:153]
	s_waitcnt lgkmcnt(2)
	v_pk_mul_f32 v[12:13], v[12:13], v[156:157]
	s_waitcnt lgkmcnt(1)
	v_pk_mul_f32 v[8:9], v[8:9], v[160:161]
	s_waitcnt lgkmcnt(0)
	v_pk_mul_f32 v[4:5], v[4:5], v[174:175]
	v_pk_mul_f32 v[14:15], v[14:15], v[150:151]
	v_pk_mul_f32 v[10:11], v[10:11], v[154:155]
	v_pk_mul_f32 v[6:7], v[6:7], v[158:159]
	v_pk_mul_f32 v[2:3], v[2:3], v[172:173]
	v_pk_mul_f32 v[64:65], v[64:65], v[152:153]
	v_pk_mul_f32 v[60:61], v[60:61], v[156:157]
	v_pk_mul_f32 v[56:57], v[56:57], v[160:161]
	v_pk_mul_f32 v[52:53], v[52:53], v[174:175]
	v_pk_mul_f32 v[62:63], v[62:63], v[150:151]
	v_pk_mul_f32 v[58:59], v[58:59], v[154:155]
	v_pk_mul_f32 v[54:55], v[54:55], v[158:159]
	v_pk_mul_f32 v[50:51], v[50:51], v[172:173]
	v_pk_mul_f32 v[48:49], v[48:49], v[152:153]
	v_pk_mul_f32 v[44:45], v[44:45], v[156:157]
	v_pk_mul_f32 v[40:41], v[40:41], v[160:161]
	v_pk_mul_f32 v[36:37], v[36:37], v[174:175]
	v_pk_mul_f32 v[46:47], v[46:47], v[150:151]
	v_pk_mul_f32 v[42:43], v[42:43], v[154:155]
	v_pk_mul_f32 v[38:39], v[38:39], v[158:159]
	v_pk_mul_f32 v[34:35], v[34:35], v[172:173]
	v_pk_mul_f32 v[32:33], v[32:33], v[152:153]
	v_pk_mul_f32 v[28:29], v[28:29], v[156:157]
	v_pk_mul_f32 v[24:25], v[24:25], v[160:161]
	v_pk_mul_f32 v[20:21], v[20:21], v[174:175]
	v_pk_mul_f32 v[30:31], v[30:31], v[150:151]
	v_pk_mul_f32 v[26:27], v[26:27], v[154:155]
	v_pk_mul_f32 v[22:23], v[22:23], v[158:159]
	v_pk_mul_f32 v[18:19], v[18:19], v[172:173]

; __device__ __forceinline__ void sel_mask_tile(f32x16& p0, f32x16& p1, unsigned wlo, unsigned whi, int hi) {
;     const unsigned NEGB = 0xff800000u;
;     const unsigned lo = wlo >> (4 * hi), h2 = whi >> (4 * hi);
; #pragma unroll
;     for (int r = 0; r < 16; ++r) {
;         const int c = (r & 3) + 8 * (r >> 2);
;         const unsigned m0 = (unsigned)__builtin_amdgcn_sbfe((int)lo, c, 1), m1 = (unsigned)__builtin_amdgcn_sbfe((int)h2, c, 1);
;         p0[r] = __uint_as_float((__float_as_uint(p0[r]) & m0) | (NEGB & ~m0));
;         p1[r] = __uint_as_float((__float_as_uint(p1[r]) & m1) | (NEGB & ~m1));
;     }
; }
; __device__ __forceinline__ void partialSM(f32x16& p0, f32x16& p1, float& m_reg, float& mn, float& alpha) {
;     float pmax = p0[0];
; #pragma unroll
;     for (int r = 1; r < 16; ++r) pmax = fmaxf(pmax, p0[r]);
; #pragma unroll
;     for (int r = 0; r < 16; ++r) pmax = fmaxf(pmax, p1[r]);
;     { auto rr = __builtin_amdgcn_permlane32_swap(__float_as_uint(pmax), __float_as_uint(pmax), false, false);
;       pmax = fmaxf(__uint_as_float(rr[0]), __uint_as_float(rr[1])); }
;     constexpr float C2 = 1.4426950408889634f * SCALE;
;     if (__builtin_expect(__all((pmax - m_reg) * SCALE <= THR), 1)) { mn = m_reg; alpha = 1.f; }
;     else { mn = fmaxf(m_reg, pmax); alpha = __builtin_amdgcn_exp2f((m_reg - mn) * C2); m_reg = mn; }
; template <int VB>
; __device__ __forceinline__ void pv_tile(f32x16* o, int vb0, bf16x8 pa0, bf16x8 pa1, bf16x8 pa2, bf16x8 pa3) {
;     ...
;     PV_D0(0); PV_D0(1); PV_D0(2); PV_D0(3);
;     ...
; }
.LBB0_1305:
	ds_read_b64_tr_b16 v[212:213], v1 offset:0x4000
	ds_read_b64_tr_b16 v[214:215], v1 offset:0x4800
	ds_read_b64_tr_b16 v[216:217], v1 offset:0x4200
	ds_read_b64_tr_b16 v[218:219], v1 offset:0x4a00
	ds_read_b64_tr_b16 v[220:221], v1 offset:0x4400
	ds_read_b64_tr_b16 v[222:223], v1 offset:0x4c00
	ds_read_b64_tr_b16 v[224:225], v1 offset:0x4600
	ds_read_b64_tr_b16 v[226:227], v1 offset:0x4e00
	ds_read_b64_tr_b16 v[232:233], v1 offset:0x5000
	ds_read_b64_tr_b16 v[234:235], v1 offset:0x5800
	ds_read_b64_tr_b16 v[236:237], v1 offset:0x5200
	ds_read_b64_tr_b16 v[238:239], v1 offset:0x5a00
	ds_read_b64_tr_b16 v[240:241], v1 offset:0x5400
	ds_read_b64_tr_b16 v[242:243], v1 offset:0x5c00
	s_nop 0
	s_waitcnt lgkmcnt(12)
	v_mfma_f32_32x32x16_bf16 v[2:17], v[146:149], v[212:215], v[2:17]
	ds_read_b64_tr_b16 v[244:245], v1 offset:0x5600
	ds_read_b64_tr_b16 v[246:247], v1 offset:0x5e00
	s_waitcnt vmcnt(4)
	v_lshrrev_b32_e32 v193, v163, v228
	v_bfe_i32 v192, v193, 0, 1
	v_bitop3_b32 v192, v82, s74, v192 bitop3:0xe4
	v_bfe_i32 v82, v193, 1, 1
	s_waitcnt lgkmcnt(12)
	v_mfma_f32_32x32x16_bf16 v[50:65], v[146:149], v[216:219], v[50:65]
	ds_read_b64_tr_b16 v[248:249], v1 offset:0x6000
	ds_read_b64_tr_b16 v[250:251], v1 offset:0x6800
	s_waitcnt lgkmcnt(12)
	v_mfma_f32_32x32x16_bf16 v[34:49], v[146:149], v[220:223], v[34:49]
	ds_read_b64_tr_b16 v[220:221], v1 offset:0x6200
	ds_read_b64_tr_b16 v[222:223], v1 offset:0x6a00
	s_waitcnt lgkmcnt(12)
	v_mfma_f32_32x32x16_bf16 v[18:33], v[146:149], v[224:227], v[18:33]
	ds_read_b64_tr_b16 v[224:225], v1 offset:0x6400
	ds_read_b64_tr_b16 v[226:227], v1 offset:0x6c00
	v_bitop3_b32 v146, v83, s74, v82 bitop3:0xe4
	v_bfe_i32 v82, v193, 2, 1
	v_bitop3_b32 v147, v84, s74, v82 bitop3:0xe4
	v_bfe_i32 v82, v193, 3, 1
	v_bitop3_b32 v148, v85, s74, v82 bitop3:0xe4
	v_bfe_i32 v82, v193, 8, 1
	v_bitop3_b32 v149, v86, s74, v82 bitop3:0xe4
	s_waitcnt lgkmcnt(12)
	v_mfma_f32_32x32x16_bf16 v[2:17], v[150:153], v[232:235], v[2:17]
	ds_read_b64_tr_b16 v[232:233], v1 offset:0x6600
	ds_read_b64_tr_b16 v[234:235], v1 offset:0x6e00
	v_bfe_i32 v82, v193, 9, 1
	s_waitcnt lgkmcnt(12)
	v_mfma_f32_32x32x16_bf16 v[50:65], v[150:153], v[236:239], v[50:65]
	ds_read_b64_tr_b16 v[236:237], v1 offset:0x7000
	ds_read_b64_tr_b16 v[238:239], v1 offset:0x7800
	s_waitcnt lgkmcnt(12)
	v_mfma_f32_32x32x16_bf16 v[34:49], v[150:153], v[240:243], v[34:49]
	ds_read_b64_tr_b16 v[240:241], v1 offset:0x7200
	ds_read_b64_tr_b16 v[242:243], v1 offset:0x7a00
	s_waitcnt lgkmcnt(12)
	v_mfma_f32_32x32x16_bf16 v[18:33], v[150:153], v[244:247], v[18:33]
	ds_read_b64_tr_b16 v[244:245], v1 offset:0x7400
	ds_read_b64_tr_b16 v[246:247], v1 offset:0x7c00
	v_bitop3_b32 v150, v87, s74, v82 bitop3:0xe4
	v_bfe_i32 v82, v193, 10, 1
	v_bitop3_b32 v88, v88, s74, v82 bitop3:0xe4
	v_bfe_i32 v82, v193, 11, 1
	v_bitop3_b32 v89, v89, s74, v82 bitop3:0xe4
	v_bfe_i32 v82, v193, 16, 1
	v_bitop3_b32 v90, v90, s74, v82 bitop3:0xe4
	v_bfe_i32 v82, v193, 17, 1
	v_bitop3_b32 v91, v91, s74, v82 bitop3:0xe4
	s_waitcnt lgkmcnt(12)
	v_mfma_f32_32x32x16_bf16 v[2:17], v[154:157], v[248:251], v[2:17]
	ds_read_b64_tr_b16 v[248:249], v1 offset:0x7600
	ds_read_b64_tr_b16 v[250:251], v1 offset:0x7e00
	v_bfe_i32 v82, v193, 18, 1
	v_bitop3_b32 v92, v92, s74, v82 bitop3:0xe4
	v_bfe_i32 v82, v193, 19, 1
	v_bitop3_b32 v93, v93, s74, v82 bitop3:0xe4
	v_bfe_i32 v82, v193, 24, 1
	v_bitop3_b32 v94, v94, s74, v82 bitop3:0xe4
	v_bfe_i32 v82, v193, 25, 1
	v_bitop3_b32 v95, v95, s74, v82 bitop3:0xe4
	v_bfe_i32 v82, v193, 26, 1
	s_waitcnt lgkmcnt(12)
	v_mfma_f32_32x32x16_bf16 v[50:65], v[154:157], v[220:223], v[50:65]
	v_bitop3_b32 v96, v96, s74, v82 bitop3:0xe4
	v_bfe_i32 v82, v193, 27, 1
	v_bitop3_b32 v97, v97, s74, v82 bitop3:0xe4
	v_max_f32_e32 v82, v146, v146
	v_max_f32_e32 v230, v192, v192
	v_max_f32_e32 v82, v230, v82
	v_max3_f32 v82, v82, v147, v148
	v_max3_f32 v82, v82, v149, v150
	v_max3_f32 v82, v82, v88, v89
	s_waitcnt lgkmcnt(10)
	v_mfma_f32_32x32x16_bf16 v[34:49], v[154:157], v[224:227], v[34:49]
	v_max3_f32 v82, v82, v90, v91
	v_lshrrev_b32_e32 v194, v163, v229
	v_max3_f32 v82, v82, v92, v93
	v_bfe_i32 v195, v194, 0, 1
	v_bfe_i32 v172, v194, 1, 1
	v_max3_f32 v82, v82, v94, v95
	v_bitop3_b32 v66, v66, s74, v195 bitop3:0xe4
	v_bfe_i32 v83, v194, 2, 1
	v_bfe_i32 v84, v194, 3, 1
	s_waitcnt lgkmcnt(8)
	v_mfma_f32_32x32x16_bf16 v[18:33], v[154:157], v[232:235], v[18:33]
	v_max3_f32 v230, v82, v96, v97
	v_bitop3_b32 v67, v67, s74, v172 bitop3:0xe4
	v_bfe_i32 v85, v194, 8, 1
	v_bfe_i32 v86, v194, 9, 1
	v_bitop3_b32 v82, v68, s74, v83 bitop3:0xe4
	v_max3_f32 v68, v230, v66, v67
	v_bitop3_b32 v83, v69, s74, v84 bitop3:0xe4
	v_bfe_i32 v87, v194, 10, 1
	v_bfe_i32 v151, v194, 11, 1
	s_waitcnt lgkmcnt(6)
	v_mfma_f32_32x32x16_bf16 v[2:17], v[158:161], v[236:239], v[2:17]
	v_bitop3_b32 v84, v70, s74, v85 bitop3:0xe4
	v_max3_f32 v68, v68, v82, v83
	v_bitop3_b32 v85, v71, s74, v86 bitop3:0xe4
	v_bfe_i32 v152, v194, 16, 1
	v_bfe_i32 v153, v194, 17, 1
	v_bitop3_b32 v86, v72, s74, v87 bitop3:0xe4
	v_max3_f32 v68, v68, v84, v85
	v_bitop3_b32 v87, v73, s74, v151 bitop3:0xe4
	v_bfe_i32 v154, v194, 18, 1
	s_waitcnt lgkmcnt(4)
	v_mfma_f32_32x32x16_bf16 v[50:65], v[158:161], v[240:243], v[50:65]
	v_bfe_i32 v155, v194, 19, 1
	v_bitop3_b32 v74, v74, s74, v152 bitop3:0xe4
	v_max3_f32 v69, v68, v86, v87
	v_bitop3_b32 v75, v75, s74, v153 bitop3:0xe4
	v_bfe_i32 v156, v194, 24, 1
	v_bfe_i32 v157, v194, 25, 1
	v_bitop3_b32 v68, v76, s74, v154 bitop3:0xe4
	v_max3_f32 v71, v69, v74, v75
	v_bitop3_b32 v69, v77, s74, v155 bitop3:0xe4
	s_waitcnt lgkmcnt(2)
	v_mfma_f32_32x32x16_bf16 v[34:49], v[158:161], v[244:247], v[34:49]
	v_bfe_i32 v230, v194, 26, 1
	v_bfe_i32 v231, v194, 27, 1
	v_bitop3_b32 v70, v78, s74, v156 bitop3:0xe4
	v_max3_f32 v73, v71, v68, v69
	v_bitop3_b32 v71, v79, s74, v157 bitop3:0xe4
	v_bitop3_b32 v72, v80, s74, v230 bitop3:0xe4
	v_max3_f32 v76, v73, v70, v71
	v_bitop3_b32 v73, v81, s74, v231 bitop3:0xe4
	v_max3_f32 v76, v76, v72, v73
	v_mov_b32_e32 v77, v76
	s_waitcnt lgkmcnt(0)
	v_mfma_f32_32x32x16_bf16 v[18:33], v[158:161], v[248:251], v[18:33]
	s_cmp_eq_u64 s[36:37], 0
	s_cbranch_scc1 .Lp5_kw2_skip
	s_waitcnt vmcnt(0)
	ds_write_b128 v204, v[138:141] offset:49152
	ds_write_b128 v204, v[142:145] offset:57344
.Lp5_kw2_skip:
	s_nop 1
	v_permlane32_swap_b32_e32 v76, v77
	v_max_f32_e32 v77, v77, v77
	v_max_f32_e32 v76, v76, v76
	v_max_f32_e32 v76, v76, v77
	v_sub_f32_e32 v77, v76, v206
	v_mul_f32_e32 v77, 0x3db504f3, v77
	v_cmp_ge_f32_e32 vcc, s75, v77
	s_cmp_eq_u64 vcc, exec
	s_cselect_b64 s[6:7], -1, 0
	s_andn2_b64 vcc, exec, s[36:37]
	s_barrier
	s_cbranch_vccnz .LBB0_1307
	s_waitcnt vmcnt(0)
	ds_write_b128 v197, v[130:133] offset:16384
	ds_write_b128 v198, v[134:137] offset:16384
